# shift@W items (phase 0b and background queue): 18 modulation loads batched, weight rows of a whole 8-step pass prefetched one pass ahead with counted vmcnt
# speedup vs baseline: 1.0173x; 1.0142x over previous
; DI u16 f2bf(float a) { return (u16)(pk2(a, 0.f) & 0xffffu); }
; DI float bf2f(u16 v) { return __uint_as_float(((unsigned)v) << 16); }
; DI void sw_item(const Params& P, unsigned char* lds, const int l, const int r, const int tid) {
;     ...
;     for (int i = tid; i < 9 * 1024; i += 512) {
;       const float v = mod[((size_t)l * 9 + (i >> 10)) * NMOD + (st * 3) * 1024 + (i & 1023)];
;       const u16 hi = f2bf(v);
;       shl[(i >> 10) * 1032 + (i & 1023)] = hi;
;       shl[9 * 1032 + (i >> 10) * 1032 + (i & 1023)] = f2bf(v - bf2f(hi));
;     }
.LBB0_29:
	s_mov_b32 s100, s8
	s_mov_b32 s101, s9
	v_lshlrev_b32_e32 v88, 2, v47
	v_lshlrev_b32_e32 v89, 1, v47
	global_load_dword v70, v88, s[100:101]
	global_load_dword v71, v88, s[100:101] offset:2048
	s_add_u32 s100, s100, 0x9000
	s_addc_u32 s101, s101, 0
	global_load_dword v72, v88, s[100:101]
	global_load_dword v73, v88, s[100:101] offset:2048
	s_add_u32 s100, s100, 0x9000
	s_addc_u32 s101, s101, 0
	global_load_dword v74, v88, s[100:101]
	global_load_dword v75, v88, s[100:101] offset:2048
	s_add_u32 s100, s100, 0x9000
	s_addc_u32 s101, s101, 0
	global_load_dword v76, v88, s[100:101]
	global_load_dword v77, v88, s[100:101] offset:2048
	s_add_u32 s100, s100, 0x9000
	s_addc_u32 s101, s101, 0
	global_load_dword v78, v88, s[100:101]
	global_load_dword v79, v88, s[100:101] offset:2048
	s_add_u32 s100, s100, 0x9000
	s_addc_u32 s101, s101, 0
	global_load_dword v80, v88, s[100:101]
	global_load_dword v81, v88, s[100:101] offset:2048
	s_add_u32 s100, s100, 0x9000
	s_addc_u32 s101, s101, 0
	global_load_dword v82, v88, s[100:101]
	global_load_dword v83, v88, s[100:101] offset:2048
	s_add_u32 s100, s100, 0x9000
	s_addc_u32 s101, s101, 0
	global_load_dword v84, v88, s[100:101]
	global_load_dword v85, v88, s[100:101] offset:2048
	s_add_u32 s100, s100, 0x9000
	s_addc_u32 s101, s101, 0
	global_load_dword v86, v88, s[100:101]
	global_load_dword v87, v88, s[100:101] offset:2048
	s_waitcnt vmcnt(17)
	v_cvt_pk_bf16_f32 v90, v70, v70
	v_lshlrev_b32_e32 v91, 16, v90
	v_sub_f32_e32 v91, v70, v91
	v_cvt_pk_bf16_f32 v91, v91, v91
	ds_write_b16 v89, v90
	ds_write_b16 v89, v91 offset:18576
	s_waitcnt vmcnt(16)
	v_cvt_pk_bf16_f32 v92, v71, v71
	v_lshlrev_b32_e32 v93, 16, v92
	v_sub_f32_e32 v93, v71, v93
	v_cvt_pk_bf16_f32 v93, v93, v93
	ds_write_b16 v89, v92 offset:1024
	ds_write_b16 v89, v93 offset:19600
	s_waitcnt vmcnt(15)
	v_cvt_pk_bf16_f32 v90, v72, v72
	v_lshlrev_b32_e32 v91, 16, v90
	v_sub_f32_e32 v91, v72, v91
	v_cvt_pk_bf16_f32 v91, v91, v91
	ds_write_b16 v89, v90 offset:2064
	ds_write_b16 v89, v91 offset:20640
	s_waitcnt vmcnt(14)
	v_cvt_pk_bf16_f32 v92, v73, v73
	v_lshlrev_b32_e32 v93, 16, v92
	v_sub_f32_e32 v93, v73, v93
	v_cvt_pk_bf16_f32 v93, v93, v93
	ds_write_b16 v89, v92 offset:3088
	ds_write_b16 v89, v93 offset:21664
	s_waitcnt vmcnt(13)
	v_cvt_pk_bf16_f32 v90, v74, v74
	v_lshlrev_b32_e32 v91, 16, v90
	v_sub_f32_e32 v91, v74, v91
	v_cvt_pk_bf16_f32 v91, v91, v91
	ds_write_b16 v89, v90 offset:4128
	ds_write_b16 v89, v91 offset:22704
	s_waitcnt vmcnt(12)
	v_cvt_pk_bf16_f32 v92, v75, v75
	v_lshlrev_b32_e32 v93, 16, v92
	v_sub_f32_e32 v93, v75, v93
	v_cvt_pk_bf16_f32 v93, v93, v93
	ds_write_b16 v89, v92 offset:5152
	ds_write_b16 v89, v93 offset:23728
	s_waitcnt vmcnt(11)
	v_cvt_pk_bf16_f32 v90, v76, v76
	v_lshlrev_b32_e32 v91, 16, v90
	v_sub_f32_e32 v91, v76, v91
	v_cvt_pk_bf16_f32 v91, v91, v91
	ds_write_b16 v89, v90 offset:6192
	ds_write_b16 v89, v91 offset:24768
	s_waitcnt vmcnt(10)
	v_cvt_pk_bf16_f32 v92, v77, v77
	v_lshlrev_b32_e32 v93, 16, v92
	v_sub_f32_e32 v93, v77, v93
	v_cvt_pk_bf16_f32 v93, v93, v93
	ds_write_b16 v89, v92 offset:7216
	ds_write_b16 v89, v93 offset:25792
	s_waitcnt vmcnt(9)
	v_cvt_pk_bf16_f32 v90, v78, v78
	v_lshlrev_b32_e32 v91, 16, v90
	v_sub_f32_e32 v91, v78, v91
	v_cvt_pk_bf16_f32 v91, v91, v91
	ds_write_b16 v89, v90 offset:8256
	ds_write_b16 v89, v91 offset:26832
	s_waitcnt vmcnt(8)
	v_cvt_pk_bf16_f32 v92, v79, v79
	v_lshlrev_b32_e32 v93, 16, v92
	v_sub_f32_e32 v93, v79, v93
	v_cvt_pk_bf16_f32 v93, v93, v93
	ds_write_b16 v89, v92 offset:9280
	ds_write_b16 v89, v93 offset:27856
	s_waitcnt vmcnt(7)
	v_cvt_pk_bf16_f32 v90, v80, v80
	v_lshlrev_b32_e32 v91, 16, v90
	v_sub_f32_e32 v91, v80, v91
	v_cvt_pk_bf16_f32 v91, v91, v91
	ds_write_b16 v89, v90 offset:10320
	ds_write_b16 v89, v91 offset:28896
	s_waitcnt vmcnt(6)
	v_cvt_pk_bf16_f32 v92, v81, v81
	v_lshlrev_b32_e32 v93, 16, v92
	v_sub_f32_e32 v93, v81, v93
	v_cvt_pk_bf16_f32 v93, v93, v93
	ds_write_b16 v89, v92 offset:11344
	ds_write_b16 v89, v93 offset:29920
	s_waitcnt vmcnt(5)
	v_cvt_pk_bf16_f32 v90, v82, v82
	v_lshlrev_b32_e32 v91, 16, v90
	v_sub_f32_e32 v91, v82, v91
	v_cvt_pk_bf16_f32 v91, v91, v91
	ds_write_b16 v89, v90 offset:12384
	ds_write_b16 v89, v91 offset:30960
	s_waitcnt vmcnt(4)
	v_cvt_pk_bf16_f32 v92, v83, v83
	v_lshlrev_b32_e32 v93, 16, v92
	v_sub_f32_e32 v93, v83, v93
	v_cvt_pk_bf16_f32 v93, v93, v93
	ds_write_b16 v89, v92 offset:13408
	ds_write_b16 v89, v93 offset:31984
	s_waitcnt vmcnt(3)
	v_cvt_pk_bf16_f32 v90, v84, v84
	v_lshlrev_b32_e32 v91, 16, v90
	v_sub_f32_e32 v91, v84, v91
	v_cvt_pk_bf16_f32 v91, v91, v91
	ds_write_b16 v89, v90 offset:14448
	ds_write_b16 v89, v91 offset:33024
	s_waitcnt vmcnt(2)
	v_cvt_pk_bf16_f32 v92, v85, v85
	v_lshlrev_b32_e32 v93, 16, v92
	v_sub_f32_e32 v93, v85, v93
	v_cvt_pk_bf16_f32 v93, v93, v93
	ds_write_b16 v89, v92 offset:15472
	ds_write_b16 v89, v93 offset:34048
	s_waitcnt vmcnt(1)
	v_cvt_pk_bf16_f32 v90, v86, v86
	v_lshlrev_b32_e32 v91, 16, v90
	v_sub_f32_e32 v91, v86, v91
	v_cvt_pk_bf16_f32 v91, v91, v91
	ds_write_b16 v89, v90 offset:16512
	ds_write_b16 v89, v91 offset:35088
	s_waitcnt vmcnt(0)
	v_cvt_pk_bf16_f32 v92, v87, v87
	v_lshlrev_b32_e32 v93, 16, v92
	v_sub_f32_e32 v93, v87, v93
	v_cvt_pk_bf16_f32 v93, v93, v93
	ds_write_b16 v89, v92 offset:17536
	ds_write_b16 v89, v93 offset:36112

; DI void sw_item(const Params& P, unsigned char* lds, const int l, const int r, const int tid) {
;     ...
;     const int n0 = ch * 256 + wave * 32;
;     const u16* wrow = wt + (size_t)(n0 + ql) * 1024 + hl * 8;
;     f32x16 acc;
; #pragma unroll
;     for (int i = 0; i < 16; ++i) acc[i] = 0.f;
; #pragma unroll 8
;     for (int kk = 0; kk < 64; ++kk) {
;       const bf16x8 aw = *(const bf16x8*)(wrow + kk * 16);
;       bf16x8 bh = (bf16x8){0, 0, 0, 0, 0, 0, 0, 0}, bl = (bf16x8){0, 0, 0, 0, 0, 0, 0, 0};
;       if (ql < 9) {
;         bh = *(const bf16x8*)(shl + ql * 1032 + kk * 16 + hl * 8);
;         bl = *(const bf16x8*)(shl + 9 * 1032 + ql * 1032 + kk * 16 + hl * 8);
;       }
;       acc = __builtin_amdgcn_mfma_f32_32x32x16_bf16(aw, bh, acc, 0, 0, 0);
;       acc = __builtin_amdgcn_mfma_f32_32x32x16_bf16(aw, bl, acc, 0, 0, 0);
;     }
.LBB0_31:
.LBB0_32:
	v_mov_b32_e32 v160, 0
	v_mov_b32_e32 v161, 0
	v_mov_b32_e32 v162, 0
	v_mov_b32_e32 v163, 0
	v_mov_b32_e32 v164, 0
	v_mov_b32_e32 v165, 0
	v_mov_b32_e32 v166, 0
	v_mov_b32_e32 v167, 0
	v_mov_b32_e32 v168, 0
	v_mov_b32_e32 v169, 0
	v_mov_b32_e32 v170, 0
	v_mov_b32_e32 v171, 0
	v_mov_b32_e32 v172, 0
	v_mov_b32_e32 v173, 0
	v_mov_b32_e32 v174, 0
	v_mov_b32_e32 v175, 0
	v_mov_b32_e32 v176, 0
	v_mov_b32_e32 v177, 0
	v_mov_b32_e32 v178, 0
	v_mov_b32_e32 v179, 0
	v_mov_b32_e32 v180, 0
	v_mov_b32_e32 v181, 0
	v_mov_b32_e32 v182, 0
	v_mov_b32_e32 v183, 0
	v_mov_b32_e32 v184, 0
	v_mov_b32_e32 v185, 0
	v_mov_b32_e32 v186, 0
	v_mov_b32_e32 v187, 0
	v_mov_b32_e32 v188, 0
	v_mov_b32_e32 v189, 0
	v_mov_b32_e32 v190, 0
	v_mov_b32_e32 v191, 0
	s_mov_b32 s100, 0x100
	s_mov_b32 s101, 0
	global_load_dwordx4 v[90:93], v[54:55], off offset:-128
	global_load_dwordx4 v[94:97], v[54:55], off offset:-96
	global_load_dwordx4 v[98:101], v[54:55], off offset:-64
	global_load_dwordx4 v[102:105], v[54:55], off offset:-32
	global_load_dwordx4 v[106:109], v[54:55], off
	global_load_dwordx4 v[110:113], v[54:55], off offset:32
	global_load_dwordx4 v[114:117], v[54:55], off offset:64
	global_load_dwordx4 v[118:121], v[54:55], off offset:96
	v_lshl_add_u64 v[54:55], v[54:55], 0, s[100:101]
.Lsw_a_trip:
	global_load_dwordx4 v[122:125], v[54:55], off offset:-128
	global_load_dwordx4 v[126:129], v[54:55], off offset:-96
	global_load_dwordx4 v[130:133], v[54:55], off offset:-64
	global_load_dwordx4 v[134:137], v[54:55], off offset:-32
	global_load_dwordx4 v[138:141], v[54:55], off
	global_load_dwordx4 v[142:145], v[54:55], off offset:32
	global_load_dwordx4 v[146:149], v[54:55], off offset:64
	global_load_dwordx4 v[150:153], v[54:55], off offset:96
	v_lshl_add_u64 v[54:55], v[54:55], 0, s[100:101]
	s_waitcnt vmcnt(8)
	v_add_u32_e32 v0, s6, v57
	s_and_saveexec_b64 s[4:5], s[38:39]
	ds_read_b128 v[160:163], v0
	ds_read_b128 v[164:167], v0 offset:18576
	ds_read_b128 v[168:171], v0 offset:32
	ds_read_b128 v[172:175], v0 offset:18608
	ds_read_b128 v[176:179], v0 offset:64
	ds_read_b128 v[180:183], v0 offset:18640
	ds_read_b128 v[184:187], v0 offset:96
	ds_read_b128 v[188:191], v0 offset:18672
	s_mov_b64 exec, s[4:5]
	s_waitcnt lgkmcnt(6)
	v_mfma_f32_32x32x16_bf16 v[2:17], v[90:93], v[160:163], v[2:17]
	v_mfma_f32_32x32x16_bf16 v[2:17], v[90:93], v[164:167], v[2:17]
	s_waitcnt lgkmcnt(4)
	v_mfma_f32_32x32x16_bf16 v[2:17], v[94:97], v[168:171], v[2:17]
	v_mfma_f32_32x32x16_bf16 v[2:17], v[94:97], v[172:175], v[2:17]
	s_waitcnt lgkmcnt(2)
	v_mfma_f32_32x32x16_bf16 v[2:17], v[98:101], v[176:179], v[2:17]
	v_mfma_f32_32x32x16_bf16 v[2:17], v[98:101], v[180:183], v[2:17]
	s_waitcnt lgkmcnt(0)
	v_mfma_f32_32x32x16_bf16 v[2:17], v[102:105], v[184:187], v[2:17]
	v_mfma_f32_32x32x16_bf16 v[2:17], v[102:105], v[188:191], v[2:17]
	s_and_saveexec_b64 s[4:5], s[38:39]
	ds_read_b128 v[160:163], v0 offset:128
	ds_read_b128 v[164:167], v0 offset:18704
	ds_read_b128 v[168:171], v0 offset:160
	ds_read_b128 v[172:175], v0 offset:18736
	ds_read_b128 v[176:179], v0 offset:192
	ds_read_b128 v[180:183], v0 offset:18768
	ds_read_b128 v[184:187], v0 offset:224
	ds_read_b128 v[188:191], v0 offset:18800
	s_mov_b64 exec, s[4:5]
	s_waitcnt lgkmcnt(6)
	v_mfma_f32_32x32x16_bf16 v[2:17], v[106:109], v[160:163], v[2:17]
	v_mfma_f32_32x32x16_bf16 v[2:17], v[106:109], v[164:167], v[2:17]
	s_waitcnt lgkmcnt(4)
	v_mfma_f32_32x32x16_bf16 v[2:17], v[110:113], v[168:171], v[2:17]
	v_mfma_f32_32x32x16_bf16 v[2:17], v[110:113], v[172:175], v[2:17]
	s_waitcnt lgkmcnt(2)
	v_mfma_f32_32x32x16_bf16 v[2:17], v[114:117], v[176:179], v[2:17]
	v_mfma_f32_32x32x16_bf16 v[2:17], v[114:117], v[180:183], v[2:17]
	s_waitcnt lgkmcnt(0)
	v_mfma_f32_32x32x16_bf16 v[2:17], v[118:121], v[184:187], v[2:17]
	v_mfma_f32_32x32x16_bf16 v[2:17], v[118:121], v[188:191], v[2:17]
	s_addk_i32 s6, 0x100
	s_cmpk_lt_u32 s6, 0x700
	s_cbranch_scc0 .Lsw_a_last
	global_load_dwordx4 v[90:93], v[54:55], off offset:-128
	global_load_dwordx4 v[94:97], v[54:55], off offset:-96
	global_load_dwordx4 v[98:101], v[54:55], off offset:-64
	global_load_dwordx4 v[102:105], v[54:55], off offset:-32
	global_load_dwordx4 v[106:109], v[54:55], off
	global_load_dwordx4 v[110:113], v[54:55], off offset:32
	global_load_dwordx4 v[114:117], v[54:55], off offset:64
	global_load_dwordx4 v[118:121], v[54:55], off offset:96
	v_lshl_add_u64 v[54:55], v[54:55], 0, s[100:101]
	s_waitcnt vmcnt(8)
	s_branch .Lsw_a_odd

; DI void sw_item(const Params& P, unsigned char* lds, const int l, const int r, const int tid) {
;     ...
; #pragma unroll 8
;     for (int kk = 0; kk < 64; ++kk) {
;       const bf16x8 aw = *(const bf16x8*)(wrow + kk * 16);
;       bf16x8 bh = (bf16x8){0, 0, 0, 0, 0, 0, 0, 0}, bl = (bf16x8){0, 0, 0, 0, 0, 0, 0, 0};
;       if (ql < 9) {
;         bh = *(const bf16x8*)(shl + ql * 1032 + kk * 16 + hl * 8);
;         bl = *(const bf16x8*)(shl + 9 * 1032 + ql * 1032 + kk * 16 + hl * 8);
;       }
;       acc = __builtin_amdgcn_mfma_f32_32x32x16_bf16(aw, bh, acc, 0, 0, 0);
;       acc = __builtin_amdgcn_mfma_f32_32x32x16_bf16(aw, bl, acc, 0, 0, 0);
;     }
.Lsw_a_odd:
	v_add_u32_e32 v0, s6, v57
	s_and_saveexec_b64 s[4:5], s[38:39]
	ds_read_b128 v[160:163], v0
	ds_read_b128 v[164:167], v0 offset:18576
	ds_read_b128 v[168:171], v0 offset:32
	ds_read_b128 v[172:175], v0 offset:18608
	ds_read_b128 v[176:179], v0 offset:64
	ds_read_b128 v[180:183], v0 offset:18640
	ds_read_b128 v[184:187], v0 offset:96
	ds_read_b128 v[188:191], v0 offset:18672
	s_mov_b64 exec, s[4:5]
	s_waitcnt lgkmcnt(6)
	v_mfma_f32_32x32x16_bf16 v[2:17], v[122:125], v[160:163], v[2:17]
	v_mfma_f32_32x32x16_bf16 v[2:17], v[122:125], v[164:167], v[2:17]
	s_waitcnt lgkmcnt(4)
	v_mfma_f32_32x32x16_bf16 v[2:17], v[126:129], v[168:171], v[2:17]
	v_mfma_f32_32x32x16_bf16 v[2:17], v[126:129], v[172:175], v[2:17]
	s_waitcnt lgkmcnt(2)
	v_mfma_f32_32x32x16_bf16 v[2:17], v[130:133], v[176:179], v[2:17]
	v_mfma_f32_32x32x16_bf16 v[2:17], v[130:133], v[180:183], v[2:17]
	s_waitcnt lgkmcnt(0)
	v_mfma_f32_32x32x16_bf16 v[2:17], v[134:137], v[184:187], v[2:17]
	v_mfma_f32_32x32x16_bf16 v[2:17], v[134:137], v[188:191], v[2:17]
	s_and_saveexec_b64 s[4:5], s[38:39]
	ds_read_b128 v[160:163], v0 offset:128
	ds_read_b128 v[164:167], v0 offset:18704
	ds_read_b128 v[168:171], v0 offset:160
	ds_read_b128 v[172:175], v0 offset:18736
	ds_read_b128 v[176:179], v0 offset:192
	ds_read_b128 v[180:183], v0 offset:18768
	ds_read_b128 v[184:187], v0 offset:224
	ds_read_b128 v[188:191], v0 offset:18800
	s_mov_b64 exec, s[4:5]
	s_waitcnt lgkmcnt(6)
	v_mfma_f32_32x32x16_bf16 v[2:17], v[138:141], v[160:163], v[2:17]
	v_mfma_f32_32x32x16_bf16 v[2:17], v[138:141], v[164:167], v[2:17]
	s_waitcnt lgkmcnt(4)
	v_mfma_f32_32x32x16_bf16 v[2:17], v[142:145], v[168:171], v[2:17]
	v_mfma_f32_32x32x16_bf16 v[2:17], v[142:145], v[172:175], v[2:17]
	s_waitcnt lgkmcnt(2)
	v_mfma_f32_32x32x16_bf16 v[2:17], v[146:149], v[176:179], v[2:17]
	v_mfma_f32_32x32x16_bf16 v[2:17], v[146:149], v[180:183], v[2:17]
	s_waitcnt lgkmcnt(0)
	v_mfma_f32_32x32x16_bf16 v[2:17], v[150:153], v[184:187], v[2:17]
	v_mfma_f32_32x32x16_bf16 v[2:17], v[150:153], v[188:191], v[2:17]
	s_addk_i32 s6, 0x100
	s_cmpk_lt_u32 s6, 0x800
	s_cbranch_scc1 .Lsw_a_trip

; DI u16 f2bf(float a) { return (u16)(pk2(a, 0.f) & 0xffffu); }
; DI float bf2f(u16 v) { return __uint_as_float(((unsigned)v) << 16); }
; DI void sw_item(const Params& P, unsigned char* lds, const int l, const int r, const int tid) {
;     ...
;     for (int i = tid; i < 9 * 1024; i += 512) {
;       const float v = mod[((size_t)l * 9 + (i >> 10)) * NMOD + (st * 3) * 1024 + (i & 1023)];
;       const u16 hi = f2bf(v);
;       shl[(i >> 10) * 1032 + (i & 1023)] = hi;
;       shl[9 * 1032 + (i >> 10) * 1032 + (i & 1023)] = f2bf(v - bf2f(hi));
;     }
.LBB0_1097:
	s_mul_i32 s6, s26, 0x9000
	s_mul_hi_u32 s7, s26, 0x9000
	s_mul_i32 s100, s27, 0x9000
	s_add_i32 s7, s7, s100
	s_add_u32 s100, s4, s6
	s_addc_u32 s101, s5, s7
	v_lshlrev_b32_e32 v88, 2, v56
	v_lshlrev_b32_e32 v89, 1, v56
	global_load_dword v70, v88, s[100:101]
	global_load_dword v71, v88, s[100:101] offset:2048
	s_add_u32 s100, s100, 0x9000
	s_addc_u32 s101, s101, 0
	global_load_dword v72, v88, s[100:101]
	global_load_dword v73, v88, s[100:101] offset:2048
	s_add_u32 s100, s100, 0x9000
	s_addc_u32 s101, s101, 0
	global_load_dword v74, v88, s[100:101]
	global_load_dword v75, v88, s[100:101] offset:2048
	s_add_u32 s100, s100, 0x9000
	s_addc_u32 s101, s101, 0
	global_load_dword v76, v88, s[100:101]
	global_load_dword v77, v88, s[100:101] offset:2048
	s_add_u32 s100, s100, 0x9000
	s_addc_u32 s101, s101, 0
	global_load_dword v78, v88, s[100:101]
	global_load_dword v79, v88, s[100:101] offset:2048
	s_add_u32 s100, s100, 0x9000
	s_addc_u32 s101, s101, 0
	global_load_dword v80, v88, s[100:101]
	global_load_dword v81, v88, s[100:101] offset:2048
	s_add_u32 s100, s100, 0x9000
	s_addc_u32 s101, s101, 0
	global_load_dword v82, v88, s[100:101]
	global_load_dword v83, v88, s[100:101] offset:2048
	s_add_u32 s100, s100, 0x9000
	s_addc_u32 s101, s101, 0
	global_load_dword v84, v88, s[100:101]
	global_load_dword v85, v88, s[100:101] offset:2048
	s_add_u32 s100, s100, 0x9000
	s_addc_u32 s101, s101, 0
	global_load_dword v86, v88, s[100:101]
	global_load_dword v87, v88, s[100:101] offset:2048
	s_waitcnt vmcnt(17)
	v_cvt_pk_bf16_f32 v90, v70, v70
	v_lshlrev_b32_e32 v91, 16, v90
	v_sub_f32_e32 v91, v70, v91
	v_cvt_pk_bf16_f32 v91, v91, v91
	ds_write_b16 v89, v90
	ds_write_b16 v89, v91 offset:18576
	s_waitcnt vmcnt(16)
	v_cvt_pk_bf16_f32 v92, v71, v71
	v_lshlrev_b32_e32 v93, 16, v92
	v_sub_f32_e32 v93, v71, v93
	v_cvt_pk_bf16_f32 v93, v93, v93
	ds_write_b16 v89, v92 offset:1024
	ds_write_b16 v89, v93 offset:19600
	s_waitcnt vmcnt(15)
	v_cvt_pk_bf16_f32 v90, v72, v72
	v_lshlrev_b32_e32 v91, 16, v90
	v_sub_f32_e32 v91, v72, v91
	v_cvt_pk_bf16_f32 v91, v91, v91
	ds_write_b16 v89, v90 offset:2064
	ds_write_b16 v89, v91 offset:20640
	s_waitcnt vmcnt(14)
	v_cvt_pk_bf16_f32 v92, v73, v73
	v_lshlrev_b32_e32 v93, 16, v92
	v_sub_f32_e32 v93, v73, v93
	v_cvt_pk_bf16_f32 v93, v93, v93
	ds_write_b16 v89, v92 offset:3088
	ds_write_b16 v89, v93 offset:21664
	s_waitcnt vmcnt(13)
	v_cvt_pk_bf16_f32 v90, v74, v74
	v_lshlrev_b32_e32 v91, 16, v90
	v_sub_f32_e32 v91, v74, v91
	v_cvt_pk_bf16_f32 v91, v91, v91
	ds_write_b16 v89, v90 offset:4128
	ds_write_b16 v89, v91 offset:22704
	s_waitcnt vmcnt(12)
	v_cvt_pk_bf16_f32 v92, v75, v75
	v_lshlrev_b32_e32 v93, 16, v92
	v_sub_f32_e32 v93, v75, v93
	v_cvt_pk_bf16_f32 v93, v93, v93
	ds_write_b16 v89, v92 offset:5152
	ds_write_b16 v89, v93 offset:23728
	s_waitcnt vmcnt(11)
	v_cvt_pk_bf16_f32 v90, v76, v76
	v_lshlrev_b32_e32 v91, 16, v90
	v_sub_f32_e32 v91, v76, v91
	v_cvt_pk_bf16_f32 v91, v91, v91
	ds_write_b16 v89, v90 offset:6192
	ds_write_b16 v89, v91 offset:24768
	s_waitcnt vmcnt(10)
	v_cvt_pk_bf16_f32 v92, v77, v77
	v_lshlrev_b32_e32 v93, 16, v92
	v_sub_f32_e32 v93, v77, v93
	v_cvt_pk_bf16_f32 v93, v93, v93
	ds_write_b16 v89, v92 offset:7216
	ds_write_b16 v89, v93 offset:25792
	s_waitcnt vmcnt(9)
	v_cvt_pk_bf16_f32 v90, v78, v78
	v_lshlrev_b32_e32 v91, 16, v90
	v_sub_f32_e32 v91, v78, v91
	v_cvt_pk_bf16_f32 v91, v91, v91
	ds_write_b16 v89, v90 offset:8256
	ds_write_b16 v89, v91 offset:26832
	s_waitcnt vmcnt(8)
	v_cvt_pk_bf16_f32 v92, v79, v79
	v_lshlrev_b32_e32 v93, 16, v92
	v_sub_f32_e32 v93, v79, v93
	v_cvt_pk_bf16_f32 v93, v93, v93
	ds_write_b16 v89, v92 offset:9280
	ds_write_b16 v89, v93 offset:27856
	s_waitcnt vmcnt(7)
	v_cvt_pk_bf16_f32 v90, v80, v80
	v_lshlrev_b32_e32 v91, 16, v90
	v_sub_f32_e32 v91, v80, v91
	v_cvt_pk_bf16_f32 v91, v91, v91
	ds_write_b16 v89, v90 offset:10320
	ds_write_b16 v89, v91 offset:28896
	s_waitcnt vmcnt(6)
	v_cvt_pk_bf16_f32 v92, v81, v81
	v_lshlrev_b32_e32 v93, 16, v92
	v_sub_f32_e32 v93, v81, v93
	v_cvt_pk_bf16_f32 v93, v93, v93
	ds_write_b16 v89, v92 offset:11344
	ds_write_b16 v89, v93 offset:29920
	s_waitcnt vmcnt(5)
	v_cvt_pk_bf16_f32 v90, v82, v82
	v_lshlrev_b32_e32 v91, 16, v90
	v_sub_f32_e32 v91, v82, v91
	v_cvt_pk_bf16_f32 v91, v91, v91
	ds_write_b16 v89, v90 offset:12384
	ds_write_b16 v89, v91 offset:30960
	s_waitcnt vmcnt(4)
	v_cvt_pk_bf16_f32 v92, v83, v83
	v_lshlrev_b32_e32 v93, 16, v92
	v_sub_f32_e32 v93, v83, v93
	v_cvt_pk_bf16_f32 v93, v93, v93
	ds_write_b16 v89, v92 offset:13408
	ds_write_b16 v89, v93 offset:31984
	s_waitcnt vmcnt(3)
	v_cvt_pk_bf16_f32 v90, v84, v84
	v_lshlrev_b32_e32 v91, 16, v90
	v_sub_f32_e32 v91, v84, v91
	v_cvt_pk_bf16_f32 v91, v91, v91
	ds_write_b16 v89, v90 offset:14448
	ds_write_b16 v89, v91 offset:33024
	s_waitcnt vmcnt(2)
	v_cvt_pk_bf16_f32 v92, v85, v85
	v_lshlrev_b32_e32 v93, 16, v92
	v_sub_f32_e32 v93, v85, v93
	v_cvt_pk_bf16_f32 v93, v93, v93
	ds_write_b16 v89, v92 offset:15472
	ds_write_b16 v89, v93 offset:34048
	s_waitcnt vmcnt(1)
	v_cvt_pk_bf16_f32 v90, v86, v86
	v_lshlrev_b32_e32 v91, 16, v90
	v_sub_f32_e32 v91, v86, v91
	v_cvt_pk_bf16_f32 v91, v91, v91
	ds_write_b16 v89, v90 offset:16512
	ds_write_b16 v89, v91 offset:35088
	s_waitcnt vmcnt(0)
	v_cvt_pk_bf16_f32 v92, v87, v87
	v_lshlrev_b32_e32 v93, 16, v92
	v_sub_f32_e32 v93, v87, v93
	v_cvt_pk_bf16_f32 v93, v93, v93
	ds_write_b16 v89, v92 offset:17536
	ds_write_b16 v89, v93 offset:36112

; DI void sw_item(const Params& P, unsigned char* lds, const int l, const int r, const int tid) {
;     ...
;     const int n0 = ch * 256 + wave * 32;
;     const u16* wrow = wt + (size_t)(n0 + ql) * 1024 + hl * 8;
;     f32x16 acc;
; #pragma unroll
;     for (int i = 0; i < 16; ++i) acc[i] = 0.f;
; #pragma unroll 8
;     for (int kk = 0; kk < 64; ++kk) {
;       const bf16x8 aw = *(const bf16x8*)(wrow + kk * 16);
;       bf16x8 bh = (bf16x8){0, 0, 0, 0, 0, 0, 0, 0}, bl = (bf16x8){0, 0, 0, 0, 0, 0, 0, 0};
;       if (ql < 9) {
;         bh = *(const bf16x8*)(shl + ql * 1032 + kk * 16 + hl * 8);
;         bl = *(const bf16x8*)(shl + 9 * 1032 + ql * 1032 + kk * 16 + hl * 8);
;       }
;       acc = __builtin_amdgcn_mfma_f32_32x32x16_bf16(aw, bh, acc, 0, 0, 0);
;       acc = __builtin_amdgcn_mfma_f32_32x32x16_bf16(aw, bl, acc, 0, 0, 0);
;     }
.LBB0_1099:
.LBB0_1100:
	v_mov_b32_e32 v160, 0
	v_mov_b32_e32 v161, 0
	v_mov_b32_e32 v162, 0
	v_mov_b32_e32 v163, 0
	v_mov_b32_e32 v164, 0
	v_mov_b32_e32 v165, 0
	v_mov_b32_e32 v166, 0
	v_mov_b32_e32 v167, 0
	v_mov_b32_e32 v168, 0
	v_mov_b32_e32 v169, 0
	v_mov_b32_e32 v170, 0
	v_mov_b32_e32 v171, 0
	v_mov_b32_e32 v172, 0
	v_mov_b32_e32 v173, 0
	v_mov_b32_e32 v174, 0
	v_mov_b32_e32 v175, 0
	v_mov_b32_e32 v176, 0
	v_mov_b32_e32 v177, 0
	v_mov_b32_e32 v178, 0
	v_mov_b32_e32 v179, 0
	v_mov_b32_e32 v180, 0
	v_mov_b32_e32 v181, 0
	v_mov_b32_e32 v182, 0
	v_mov_b32_e32 v183, 0
	v_mov_b32_e32 v184, 0
	v_mov_b32_e32 v185, 0
	v_mov_b32_e32 v186, 0
	v_mov_b32_e32 v187, 0
	v_mov_b32_e32 v188, 0
	v_mov_b32_e32 v189, 0
	v_mov_b32_e32 v190, 0
	v_mov_b32_e32 v191, 0
	s_mov_b32 s100, 0x100
	s_mov_b32 s101, 0
	global_load_dwordx4 v[90:93], v[36:37], off offset:-128
	global_load_dwordx4 v[94:97], v[36:37], off offset:-96
	global_load_dwordx4 v[98:101], v[36:37], off offset:-64
	global_load_dwordx4 v[102:105], v[36:37], off offset:-32
	global_load_dwordx4 v[106:109], v[36:37], off
	global_load_dwordx4 v[110:113], v[36:37], off offset:32
	global_load_dwordx4 v[114:117], v[36:37], off offset:64
	global_load_dwordx4 v[118:121], v[36:37], off offset:96
	v_lshl_add_u64 v[36:37], v[36:37], 0, s[100:101]
.Lsw_b_trip:
	global_load_dwordx4 v[122:125], v[36:37], off offset:-128
	global_load_dwordx4 v[126:129], v[36:37], off offset:-96
	global_load_dwordx4 v[130:133], v[36:37], off offset:-64
	global_load_dwordx4 v[134:137], v[36:37], off offset:-32
	global_load_dwordx4 v[138:141], v[36:37], off
	global_load_dwordx4 v[142:145], v[36:37], off offset:32
	global_load_dwordx4 v[146:149], v[36:37], off offset:64
	global_load_dwordx4 v[150:153], v[36:37], off offset:96
	v_lshl_add_u64 v[36:37], v[36:37], 0, s[100:101]
	s_waitcnt vmcnt(8)
	v_add_u32_e32 v35, s2, v33
	s_and_saveexec_b64 s[0:1], vcc
	ds_read_b128 v[160:163], v35
	ds_read_b128 v[164:167], v35 offset:18576
	ds_read_b128 v[168:171], v35 offset:32
	ds_read_b128 v[172:175], v35 offset:18608
	ds_read_b128 v[176:179], v35 offset:64
	ds_read_b128 v[180:183], v35 offset:18640
	ds_read_b128 v[184:187], v35 offset:96
	ds_read_b128 v[188:191], v35 offset:18672
	s_mov_b64 exec, s[0:1]
	s_waitcnt lgkmcnt(6)
	v_mfma_f32_32x32x16_bf16 v[2:17], v[90:93], v[160:163], v[2:17]
	v_mfma_f32_32x32x16_bf16 v[2:17], v[90:93], v[164:167], v[2:17]
	s_waitcnt lgkmcnt(4)
	v_mfma_f32_32x32x16_bf16 v[2:17], v[94:97], v[168:171], v[2:17]
	v_mfma_f32_32x32x16_bf16 v[2:17], v[94:97], v[172:175], v[2:17]
	s_waitcnt lgkmcnt(2)
	v_mfma_f32_32x32x16_bf16 v[2:17], v[98:101], v[176:179], v[2:17]
	v_mfma_f32_32x32x16_bf16 v[2:17], v[98:101], v[180:183], v[2:17]
	s_waitcnt lgkmcnt(0)
	v_mfma_f32_32x32x16_bf16 v[2:17], v[102:105], v[184:187], v[2:17]
	v_mfma_f32_32x32x16_bf16 v[2:17], v[102:105], v[188:191], v[2:17]
	s_and_saveexec_b64 s[0:1], vcc
	ds_read_b128 v[160:163], v35 offset:128
	ds_read_b128 v[164:167], v35 offset:18704
	ds_read_b128 v[168:171], v35 offset:160
	ds_read_b128 v[172:175], v35 offset:18736
	ds_read_b128 v[176:179], v35 offset:192
	ds_read_b128 v[180:183], v35 offset:18768
	ds_read_b128 v[184:187], v35 offset:224
	ds_read_b128 v[188:191], v35 offset:18800
	s_mov_b64 exec, s[0:1]
	s_waitcnt lgkmcnt(6)
	v_mfma_f32_32x32x16_bf16 v[2:17], v[106:109], v[160:163], v[2:17]
	v_mfma_f32_32x32x16_bf16 v[2:17], v[106:109], v[164:167], v[2:17]
	s_waitcnt lgkmcnt(4)
	v_mfma_f32_32x32x16_bf16 v[2:17], v[110:113], v[168:171], v[2:17]
	v_mfma_f32_32x32x16_bf16 v[2:17], v[110:113], v[172:175], v[2:17]
	s_waitcnt lgkmcnt(2)
	v_mfma_f32_32x32x16_bf16 v[2:17], v[114:117], v[176:179], v[2:17]
	v_mfma_f32_32x32x16_bf16 v[2:17], v[114:117], v[180:183], v[2:17]
	s_waitcnt lgkmcnt(0)
	v_mfma_f32_32x32x16_bf16 v[2:17], v[118:121], v[184:187], v[2:17]
	v_mfma_f32_32x32x16_bf16 v[2:17], v[118:121], v[188:191], v[2:17]
	s_addk_i32 s2, 0x100
	s_cmpk_lt_u32 s2, 0x700
	s_cbranch_scc0 .Lsw_b_last
	global_load_dwordx4 v[90:93], v[36:37], off offset:-128
	global_load_dwordx4 v[94:97], v[36:37], off offset:-96
	global_load_dwordx4 v[98:101], v[36:37], off offset:-64
	global_load_dwordx4 v[102:105], v[36:37], off offset:-32
	global_load_dwordx4 v[106:109], v[36:37], off
	global_load_dwordx4 v[110:113], v[36:37], off offset:32
	global_load_dwordx4 v[114:117], v[36:37], off offset:64
	global_load_dwordx4 v[118:121], v[36:37], off offset:96
	v_lshl_add_u64 v[36:37], v[36:37], 0, s[100:101]
	s_waitcnt vmcnt(8)
	s_branch .Lsw_b_odd

; DI void sw_item(const Params& P, unsigned char* lds, const int l, const int r, const int tid) {
;     ...
; #pragma unroll 8
;     for (int kk = 0; kk < 64; ++kk) {
;       const bf16x8 aw = *(const bf16x8*)(wrow + kk * 16);
;       bf16x8 bh = (bf16x8){0, 0, 0, 0, 0, 0, 0, 0}, bl = (bf16x8){0, 0, 0, 0, 0, 0, 0, 0};
;       if (ql < 9) {
;         bh = *(const bf16x8*)(shl + ql * 1032 + kk * 16 + hl * 8);
;         bl = *(const bf16x8*)(shl + 9 * 1032 + ql * 1032 + kk * 16 + hl * 8);
;       }
;       acc = __builtin_amdgcn_mfma_f32_32x32x16_bf16(aw, bh, acc, 0, 0, 0);
;       acc = __builtin_amdgcn_mfma_f32_32x32x16_bf16(aw, bl, acc, 0, 0, 0);
;     }
.Lsw_b_odd:
	v_add_u32_e32 v35, s2, v33
	s_and_saveexec_b64 s[0:1], vcc
	ds_read_b128 v[160:163], v35
	ds_read_b128 v[164:167], v35 offset:18576
	ds_read_b128 v[168:171], v35 offset:32
	ds_read_b128 v[172:175], v35 offset:18608
	ds_read_b128 v[176:179], v35 offset:64
	ds_read_b128 v[180:183], v35 offset:18640
	ds_read_b128 v[184:187], v35 offset:96
	ds_read_b128 v[188:191], v35 offset:18672
	s_mov_b64 exec, s[0:1]
	s_waitcnt lgkmcnt(6)
	v_mfma_f32_32x32x16_bf16 v[2:17], v[122:125], v[160:163], v[2:17]
	v_mfma_f32_32x32x16_bf16 v[2:17], v[122:125], v[164:167], v[2:17]
	s_waitcnt lgkmcnt(4)
	v_mfma_f32_32x32x16_bf16 v[2:17], v[126:129], v[168:171], v[2:17]
	v_mfma_f32_32x32x16_bf16 v[2:17], v[126:129], v[172:175], v[2:17]
	s_waitcnt lgkmcnt(2)
	v_mfma_f32_32x32x16_bf16 v[2:17], v[130:133], v[176:179], v[2:17]
	v_mfma_f32_32x32x16_bf16 v[2:17], v[130:133], v[180:183], v[2:17]
	s_waitcnt lgkmcnt(0)
	v_mfma_f32_32x32x16_bf16 v[2:17], v[134:137], v[184:187], v[2:17]
	v_mfma_f32_32x32x16_bf16 v[2:17], v[134:137], v[188:191], v[2:17]
	s_and_saveexec_b64 s[0:1], vcc
	ds_read_b128 v[160:163], v35 offset:128
	ds_read_b128 v[164:167], v35 offset:18704
	ds_read_b128 v[168:171], v35 offset:160
	ds_read_b128 v[172:175], v35 offset:18736
	ds_read_b128 v[176:179], v35 offset:192
	ds_read_b128 v[180:183], v35 offset:18768
	ds_read_b128 v[184:187], v35 offset:224
	ds_read_b128 v[188:191], v35 offset:18800
	s_mov_b64 exec, s[0:1]
	s_waitcnt lgkmcnt(6)
	v_mfma_f32_32x32x16_bf16 v[2:17], v[138:141], v[160:163], v[2:17]
	v_mfma_f32_32x32x16_bf16 v[2:17], v[138:141], v[164:167], v[2:17]
	s_waitcnt lgkmcnt(4)
	v_mfma_f32_32x32x16_bf16 v[2:17], v[142:145], v[168:171], v[2:17]
	v_mfma_f32_32x32x16_bf16 v[2:17], v[142:145], v[172:175], v[2:17]
	s_waitcnt lgkmcnt(2)
	v_mfma_f32_32x32x16_bf16 v[2:17], v[146:149], v[176:179], v[2:17]
	v_mfma_f32_32x32x16_bf16 v[2:17], v[146:149], v[180:183], v[2:17]
	s_waitcnt lgkmcnt(0)
	v_mfma_f32_32x32x16_bf16 v[2:17], v[150:153], v[184:187], v[2:17]
	v_mfma_f32_32x32x16_bf16 v[2:17], v[150:153], v[188:191], v[2:17]
	s_addk_i32 s2, 0x100
	s_cmpk_lt_u32 s2, 0x800
	s_cbranch_scc1 .Lsw_b_trip
